# Grid barrier: members poll their XCD's release word with L1-bypassing L2-scope loads, every eighth poll at device scope as before
# baseline (speedup 1.0000x reference)
.LBB0_99:
	v_mov_b64_e32 v[0:1], s[6:7]
	s_and_b32 s20, s28, 7
	s_cmp_eq_u32 s20, 0
	s_cbranch_scc1 .Lbarp1_1
	flat_load_dword v0, v[0:1] sc0
	s_branch .Lbarpj_1
.Lbarp1_1:
	flat_load_dword v0, v[0:1] sc1
.Lbarpj_1:
	s_add_i32 s28, s28, 1
	s_or_b64 s[20:21], s[20:21], exec
	s_waitcnt vmcnt(0) lgkmcnt(0)
	v_cmp_ne_u32_e32 vcc, v0, v2
	s_orn2_b64 s[24:25], vcc, exec
	s_branch .LBB0_93

.LBB0_304:
	v_mov_b64_e32 v[0:1], s[6:7]
	s_and_b32 s20, s26, 7
	s_cmp_eq_u32 s20, 0
	s_cbranch_scc1 .Lbarp1_2
	flat_load_dword v0, v[0:1] sc0
	s_branch .Lbarpj_2

.Lbarpj_2:
	s_add_i32 s26, s26, 1
	s_or_b64 s[20:21], s[20:21], exec
	s_waitcnt vmcnt(0) lgkmcnt(0)
	v_cmp_ne_u32_e32 vcc, v0, v2
	s_orn2_b64 s[18:19], vcc, exec
	s_branch .LBB0_298

.LBB0_381:
	v_mov_b64_e32 v[0:1], s[6:7]
	s_and_b32 s9, s8, 7
	s_cmp_eq_u32 s9, 0
	s_cbranch_scc1 .Lbarp1_3
	flat_load_dword v0, v[0:1] sc0
	s_branch .Lbarpj_3

.Lbarpj_3:
	s_add_i32 s8, s8, 1
	s_or_b64 s[20:21], s[20:21], exec
	s_waitcnt vmcnt(0) lgkmcnt(0)
	v_cmp_ne_u32_e32 vcc, v0, v2
	s_orn2_b64 s[18:19], vcc, exec
	s_branch .LBB0_375

.Lbarpj_5:
	s_add_i32 s8, s8, 1
	s_or_b64 s[22:23], s[22:23], exec
	s_waitcnt vmcnt(0) lgkmcnt(0)
	v_cmp_ne_u32_e32 vcc, v0, v2
	s_orn2_b64 s[20:21], vcc, exec
	s_branch .LBB0_536

.LBB0_971:
	v_mov_b64_e32 v[0:1], s[10:11]
	s_and_b32 s22, s29, 7
	s_cmp_eq_u32 s22, 0
	s_cbranch_scc1 .Lbarp1_7
	flat_load_dword v0, v[0:1] sc0
	s_branch .Lbarpj_7

.Lbarpj_7:
	s_add_i32 s29, s29, 1
	s_or_b64 s[22:23], s[22:23], exec
	s_waitcnt vmcnt(0) lgkmcnt(0)
	v_cmp_ne_u32_e32 vcc, v0, v2
	s_orn2_b64 s[20:21], vcc, exec
	s_branch .LBB0_965

.LBB0_1022:
	v_mov_b64_e32 v[0:1], s[12:13]
	s_and_b32 s9, s8, 7
	s_cmp_eq_u32 s9, 0
	s_cbranch_scc1 .Lbarp1_8
	flat_load_dword v0, v[0:1] sc0
	s_branch .Lbarpj_8

.Lbarpj_8:
	s_add_i32 s8, s8, 1
	s_or_b64 s[24:25], s[24:25], exec
	s_waitcnt vmcnt(0) lgkmcnt(0)
	v_cmp_ne_u32_e32 vcc, v0, v2
	s_orn2_b64 s[22:23], vcc, exec
	s_branch .LBB0_1016
